# P10 final output stores marked nt (streaming) so the last phase's dirty lines drain before kernel end
# baseline (speedup 1.0000x reference)
; __device__ __forceinline__ float bf2f(unsigned b) { return __uint_as_float(b << 16); }
; __device__ __forceinline__ float sigmoidf_(float x) { return __builtin_amdgcn_rcpf(1.f + __expf(-x)); }
; __device__ __forceinline__ void row_final2(const FinPtrs (&r)[NR], const float* g, int lane) {
;     ...
; #pragma unroll
;     for (int k = 0; k < NR; ++k) { ss[k] = 0.f;
; #pragma unroll
;         for (int j = 0; j < 4; ++j) {
;             f32x4 pe, gl;
;             { const u32x2 a = ra[k][j]; pe = (f32x4){bf2f(a.x & 0xffffu), bf2f(a.x >> 16), bf2f(a.y & 0xffffu), bf2f(a.y >> 16)}; }
;             if (r[k].gls == nullptr) { const u32x2 b = rb[k][j]; gl = (f32x4){bf2f(b.x & 0xffffu), bf2f(b.x >> 16), bf2f(b.y & 0xffffu), bf2f(b.y >> 16)}; }
;             else { const float* gls = r[k].gls;
;                 gl = (((const f32x4*)gls)[lane + 64 * j] + ((const f32x4*)(gls + (size_t)TS * D))[lane + 64 * j]) + (((const f32x4*)(gls + (size_t)2 * TS * D))[lane + 64 * j] + ((const f32x4*)(gls + (size_t)3 * TS * D))[lane + 64 * j]); }
;             z[k][j] = (f32x4){pe.x * sigmoidf_(gl.x), pe.y * sigmoidf_(gl.y), pe.z * sigmoidf_(gl.z), pe.w * sigmoidf_(gl.w)};
;             ss[k] += (z[k][j].x * z[k][j].x + z[k][j].y * z[k][j].y) + (z[k][j].z * z[k][j].z + z[k][j].w * z[k][j].w);
;         } }
; #pragma unroll
;     for (int o = 1; o < 64; o <<= 1) {
; #pragma unroll
;             for (int k = 0; k < NR; ++k) ss[k] += __shfl_xor(ss[k], o); }
; #pragma unroll
;     for (int k = 0; k < NR; ++k) { const float rs = rsqrtf(ss[k] * (1.f / D) + EPS);
.LBB0_1209:
	v_mul_f32_e32 v20, 0xbfb8aa3b, v20
	v_mul_f32_e32 v21, 0xbfb8aa3b, v21
	v_mul_f32_e32 v22, 0xbfb8aa3b, v22
	v_exp_f32_e32 v20, v20
	v_exp_f32_e32 v21, v21
	v_exp_f32_e32 v22, v22
	v_mul_f32_e32 v23, 0xbfb8aa3b, v23
	v_exp_f32_e32 v23, v23
	v_add_f32_e32 v20, 1.0, v20
	v_add_f32_e32 v21, 1.0, v21
	v_add_f32_e32 v22, 1.0, v22
	v_rcp_f32_e32 v20, v20
	v_rcp_f32_e32 v21, v21
	v_rcp_f32_e32 v116, v22
	v_add_f32_e32 v22, 1.0, v23
	v_rcp_f32_e32 v117, v22
	v_lshlrev_b32_e32 v110, 16, v108
	v_and_b32_e32 v111, 0xffff0000, v108
	v_pk_mul_f32 v[22:23], v[20:21], v[110:111]
	v_lshlrev_b32_e32 v20, 16, v109
	v_and_b32_e32 v21, 0xffff0000, v109
	v_pk_mul_f32 v[108:109], v[116:117], v[20:21]
	v_mov_b32_e32 v110, v23
	v_mov_b32_e32 v111, v109
	v_mov_b32_e32 v20, v22
	v_mov_b32_e32 v21, v108
	v_pk_mul_f32 v[110:111], v[110:111], v[110:111]
	v_mul_f32_e32 v24, 0xbfb8aa3b, v24
	v_pk_fma_f32 v[20:21], v[20:21], v[20:21], v[110:111]
	v_exp_f32_e32 v110, v24
	v_mul_f32_e32 v24, 0xbfb8aa3b, v25
	v_exp_f32_e32 v111, v24
	v_pk_add_f32 v[24:25], v[20:21], v[20:21] op_sel:[0,1] op_sel_hi:[1,0]
	v_add_f32_e32 v20, 1.0, v110
	v_mul_f32_e32 v25, 0xbfb8aa3b, v26
	v_exp_f32_e32 v25, v25
	v_mul_f32_e32 v26, 0xbfb8aa3b, v27
	v_exp_f32_e32 v26, v26
	v_add_f32_e32 v21, 1.0, v111
	v_add_f32_e32 v25, 1.0, v25
	v_rcp_f32_e32 v116, v25
	v_add_f32_e32 v25, 1.0, v26
	v_rcp_f32_e32 v117, v25
	v_mul_f32_e32 v25, 0xbfb8aa3b, v28
	v_rcp_f32_e32 v20, v20
	v_rcp_f32_e32 v21, v21
	v_exp_f32_e32 v25, v25
	v_mul_f32_e32 v28, 0xbfb8aa3b, v29
	v_exp_f32_e32 v29, v28
	v_lshlrev_b32_e32 v110, 16, v106
	v_and_b32_e32 v111, 0xffff0000, v106
	v_pk_mul_f32 v[26:27], v[20:21], v[110:111]
	v_lshlrev_b32_e32 v20, 16, v107
	v_and_b32_e32 v21, 0xffff0000, v107
	v_add_f32_e32 v25, 1.0, v25
	v_pk_mul_f32 v[106:107], v[116:117], v[20:21]
	v_rcp_f32_e32 v28, v25
	v_add_f32_e32 v25, 1.0, v29
	v_mov_b32_e32 v110, v27
	v_mov_b32_e32 v111, v107
	v_rcp_f32_e32 v29, v25
	v_mov_b32_e32 v20, v26
	v_mov_b32_e32 v21, v106
	v_pk_mul_f32 v[110:111], v[110:111], v[110:111]
	v_mul_f32_e32 v25, 0xbfb8aa3b, v30
	v_pk_fma_f32 v[20:21], v[20:21], v[20:21], v[110:111]
	v_exp_f32_e32 v25, v25
	v_pk_add_f32 v[110:111], v[20:21], v[20:21] op_sel:[0,1] op_sel_hi:[1,0]
	v_lshlrev_b32_e32 v20, 16, v104
	v_and_b32_e32 v21, 0xffff0000, v104
	v_pk_mul_f32 v[20:21], v[28:29], v[20:21]
	v_mul_f32_e32 v28, 0xbfb8aa3b, v31
	s_nop 0
	v_exp_f32_e32 v29, v28
	v_add_f32_e32 v25, 1.0, v25
	v_rcp_f32_e32 v30, v25
	v_mul_f32_e32 v28, v21, v21
	v_add_f32_e32 v25, 1.0, v29
	v_rcp_f32_e32 v31, v25
	v_mul_f32_e32 v16, 0xbfb8aa3b, v16
	v_pk_fma_f32 v[120:121], v[20:21], v[20:21], v[28:29] op_sel_hi:[1,1,0]
	v_lshlrev_b32_e32 v28, 16, v105
	v_and_b32_e32 v29, 0xffff0000, v105
	v_exp_f32_e32 v25, v16
	v_mul_f32_e32 v16, 0xbfb8aa3b, v17
	v_pk_mul_f32 v[28:29], v[30:31], v[28:29]
	v_exp_f32_e32 v31, v16
	v_mul_f32_e32 v30, v29, v29
	v_lshlrev_b32_e32 v104, 16, v96
	v_and_b32_e32 v105, 0xffff0000, v96
	v_pk_fma_f32 v[16:17], v[28:29], v[28:29], v[30:31] op_sel_hi:[1,1,0]
	v_lshlrev_b32_e32 v96, 16, v97
	v_add_f32_e32 v17, 1.0, v25
	v_rcp_f32_e32 v30, v17
	v_add_f32_e32 v17, 1.0, v31
	v_rcp_f32_e32 v31, v17
	v_mul_f32_e32 v17, 0xbfb8aa3b, v18
	v_exp_f32_e32 v17, v17
	v_mul_f32_e32 v18, 0xbfb8aa3b, v19
	v_exp_f32_e32 v19, v18
	v_and_b32_e32 v97, 0xffff0000, v97
	v_add_f32_e32 v17, 1.0, v17
	v_rcp_f32_e32 v18, v17
	v_add_f32_e32 v17, 1.0, v19
	v_rcp_f32_e32 v19, v17
	v_pk_mul_f32 v[104:105], v[30:31], v[104:105]
	v_mul_f32_e32 v0, 0xbfb8aa3b, v0
	v_pk_mul_f32 v[30:31], v[104:105], v[104:105]
	v_pk_mul_f32 v[96:97], v[18:19], v[96:97]
	v_mov_b32_e32 v25, v30
	v_pk_mul_f32 v[18:19], v[96:97], v[96:97]
	v_mov_b32_e32 v111, v31
	v_mov_b32_e32 v121, v18
	v_mov_b32_e32 v17, v19
	v_pk_add_f32 v[24:25], v[24:25], v[110:111]
	v_pk_add_f32 v[16:17], v[120:121], v[16:17]
	v_and_b32_e32 v19, 0xffff0000, v89
	v_pk_add_f32 v[16:17], v[24:25], v[16:17]
	v_mul_f32_e32 v1, 0xbfb8aa3b, v1
	v_add_f32_e32 v16, v16, v17
	ds_bpermute_b32 v17, v49, v16
	v_exp_f32_e32 v0, v0
	v_exp_f32_e32 v1, v1
	v_mul_f32_e32 v2, 0xbfb8aa3b, v2
	v_mul_f32_e32 v3, 0xbfb8aa3b, v3
	s_waitcnt lgkmcnt(0)
	v_add_f32_e32 v16, v16, v17
	ds_bpermute_b32 v17, v51, v16
	v_exp_f32_e32 v2, v2
	v_exp_f32_e32 v3, v3
	v_add_f32_e32 v0, 1.0, v0
	v_add_f32_e32 v1, 1.0, v1
	s_waitcnt lgkmcnt(0)
	v_add_f32_e32 v16, v16, v17
	ds_bpermute_b32 v17, v61, v16
	v_rcp_f32_e32 v0, v0
	v_rcp_f32_e32 v1, v1
	v_add_f32_e32 v2, 1.0, v2
	v_add_f32_e32 v3, 1.0, v3
	s_waitcnt lgkmcnt(0)
	v_add_f32_e32 v16, v16, v17
	ds_bpermute_b32 v17, v112, v16
	v_rcp_f32_e32 v2, v2
	v_rcp_f32_e32 v3, v3
	s_lshl_b64 s[0:1], s[10:11], 12
	s_add_i32 s34, s96, s33
	s_waitcnt lgkmcnt(0)
	v_add_f32_e32 v16, v16, v17
	ds_bpermute_b32 v17, v113, v16
	v_lshl_add_u64 v[58:59], v[58:59], 0, s[18:19]
	s_waitcnt lgkmcnt(0)
	v_add_f32_e32 v17, v16, v17
	ds_bpermute_b32 v18, v114, v17
	v_lshlrev_b32_e32 v16, 16, v88
	s_waitcnt lgkmcnt(0)
	v_add_f32_e32 v17, v17, v18
	v_fmamk_f32 v17, v17, 0x3a800000, v60
	v_mul_f32_e32 v18, 0x4b800000, v17
	v_cmp_gt_f32_e32 vcc, s9, v17
	s_nop 1
	v_cndmask_b32_e32 v17, v17, v18, vcc
	v_rsq_f32_e32 v24, v17
	v_and_b32_e32 v17, 0xffff0000, v88
	v_lshlrev_b32_e32 v18, 16, v89
	v_mul_f32_e32 v25, 0x45800000, v24
	v_cndmask_b32_e32 v88, v24, v25, vcc
	v_pk_mul_f32 v[22:23], v[22:23], v[88:89] op_sel_hi:[1,0]
	v_pk_mul_f32 v[24:25], v[108:109], v[88:89] op_sel_hi:[1,0]
	s_waitcnt vmcnt(0)
; __device__ __forceinline__ float bf2f(unsigned b) { return __uint_as_float(b << 16); }
; __device__ __forceinline__ float sigmoidf_(float x) { return __builtin_amdgcn_rcpf(1.f + __expf(-x)); }
; __device__ __forceinline__ void row_final2(const FinPtrs (&r)[NR], const float* g, int lane) {
;     ...
;         for (int j = 0; j < 4; ++j) {
;             f32x4 pe, gl;
;             { const u32x2 a = ra[k][j]; pe = (f32x4){bf2f(a.x & 0xffffu), bf2f(a.x >> 16), bf2f(a.y & 0xffffu), bf2f(a.y >> 16)}; }
;             if (r[k].gls == nullptr) { const u32x2 b = rb[k][j]; gl = (f32x4){bf2f(b.x & 0xffffu), bf2f(b.x >> 16), bf2f(b.y & 0xffffu), bf2f(b.y >> 16)}; }
;             else { const float* gls = r[k].gls;
;                 gl = (((const f32x4*)gls)[lane + 64 * j] + ((const f32x4*)(gls + (size_t)TS * D))[lane + 64 * j]) + (((const f32x4*)(gls + (size_t)2 * TS * D))[lane + 64 * j] + ((const f32x4*)(gls + (size_t)3 * TS * D))[lane + 64 * j]); }
;             z[k][j] = (f32x4){pe.x * sigmoidf_(gl.x), pe.y * sigmoidf_(gl.y), pe.z * sigmoidf_(gl.z), pe.w * sigmoidf_(gl.w)};
;             ss[k] += (z[k][j].x * z[k][j].x + z[k][j].y * z[k][j].y) + (z[k][j].z * z[k][j].z + z[k][j].w * z[k][j].w);
;         } }
; #pragma unroll
;     for (int o = 1; o < 64; o <<= 1) {
; #pragma unroll
;             for (int k = 0; k < NR; ++k) ss[k] += __shfl_xor(ss[k], o); }
; #pragma unroll
;     for (int k = 0; k < NR; ++k) { const float rs = rsqrtf(ss[k] * (1.f / D) + EPS);
; #pragma unroll
;         for (int j = 0; j < 4; ++j) { const f32x4 gv = ((const f32x4*)g)[lane + 64 * j]; ((f32x4*)r[k].yout)[lane + 64 * j] = x[k][j] + z[k][j] * rs * gv; } }
	v_pk_fma_f32 v[16:17], v[240:241], v[22:23], v[16:17]
	v_pk_fma_f32 v[18:19], v[242:243], v[24:25], v[18:19]
	global_store_dwordx4 v[56:57], v[16:19], off nt
	s_nop 0
	v_pk_mul_f32 v[26:27], v[26:27], v[88:89] op_sel_hi:[1,0]
	v_mul_f32_e32 v16, 0xbfb8aa3b, v36
	v_mul_f32_e32 v17, 0xbfb8aa3b, v37
	v_mul_f32_e32 v19, 0xbfb8aa3b, v38
	v_exp_f32_e32 v16, v16
	v_exp_f32_e32 v17, v17
	v_exp_f32_e32 v22, v19
	v_mul_f32_e32 v19, 0xbfb8aa3b, v39
	v_exp_f32_e32 v23, v19
	v_add_f32_e32 v16, 1.0, v16
	v_add_f32_e32 v17, 1.0, v17
	v_rcp_f32_e32 v16, v16
	v_rcp_f32_e32 v17, v17
	v_add_f32_e32 v22, 1.0, v22
	v_add_f32_e32 v23, 1.0, v23
	v_rcp_f32_e32 v22, v22
	v_rcp_f32_e32 v23, v23
	v_lshlrev_b32_e32 v18, 16, v100
	v_and_b32_e32 v19, 0xffff0000, v100
	v_pk_mul_f32 v[16:17], v[16:17], v[18:19]
	v_lshlrev_b32_e32 v18, 16, v101
	v_and_b32_e32 v19, 0xffff0000, v101
	v_pk_mul_f32 v[18:19], v[22:23], v[18:19]
	v_mov_b32_e32 v24, v17
	v_mov_b32_e32 v25, v19
	v_mov_b32_e32 v22, v16
	v_mov_b32_e32 v23, v18
	v_pk_mul_f32 v[24:25], v[24:25], v[24:25]
	v_mul_f32_e32 v37, 0xbfb8aa3b, v44
	v_pk_fma_f32 v[22:23], v[22:23], v[22:23], v[24:25]
	v_mul_f32_e32 v25, 0xbfb8aa3b, v41
	v_exp_f32_e32 v25, v25
	v_mul_f32_e32 v24, 0xbfb8aa3b, v40
	v_pk_add_f32 v[40:41], v[22:23], v[22:23] op_sel:[0,1] op_sel_hi:[1,0]
	v_exp_f32_e32 v24, v24
	v_add_f32_e32 v23, 1.0, v25
	v_mul_f32_e32 v25, 0xbfb8aa3b, v42
	v_exp_f32_e32 v30, v25
	v_mul_f32_e32 v25, 0xbfb8aa3b, v43
	v_exp_f32_e32 v31, v25
	v_add_f32_e32 v22, 1.0, v24
	v_rcp_f32_e32 v22, v22
	v_rcp_f32_e32 v23, v23
	v_add_f32_e32 v30, 1.0, v30
	v_add_f32_e32 v31, 1.0, v31
	v_rcp_f32_e32 v30, v30
	v_rcp_f32_e32 v31, v31
	v_lshlrev_b32_e32 v24, 16, v102
	v_and_b32_e32 v25, 0xffff0000, v102
	v_pk_mul_f32 v[22:23], v[22:23], v[24:25]
	v_lshlrev_b32_e32 v24, 16, v103
	v_and_b32_e32 v25, 0xffff0000, v103
	v_exp_f32_e32 v38, v37
	v_pk_mul_f32 v[24:25], v[30:31], v[24:25]
	v_mov_b32_e32 v36, v23
	v_mov_b32_e32 v37, v25
	v_mov_b32_e32 v30, v22
	v_mov_b32_e32 v31, v24
	v_pk_mul_f32 v[36:37], v[36:37], v[36:37]
	v_and_b32_e32 v39, 0xffff0000, v83
	v_pk_fma_f32 v[30:31], v[30:31], v[30:31], v[36:37]
	v_add_f32_e32 v36, 1.0, v38
	v_rcp_f32_e32 v42, v36
	v_mul_f32_e32 v36, 0xbfb8aa3b, v45
	v_exp_f32_e32 v41, v36
	v_lshlrev_b32_e32 v36, 16, v82
	v_and_b32_e32 v37, 0xffff0000, v82
	v_lshlrev_b32_e32 v38, 16, v83
	v_pk_mul_f32 v[44:45], v[106:107], v[88:89] op_sel_hi:[1,0]
	v_lshlrev_b32_e32 v82, 16, v90
	v_and_b32_e32 v83, 0xffff0000, v90
	v_pk_mul_f32 v[82:83], v[0:1], v[82:83]
	v_lshlrev_b32_e32 v0, 16, v91
	v_and_b32_e32 v1, 0xffff0000, v91
	v_pk_mul_f32 v[90:91], v[2:3], v[0:1]
	v_mov_b32_e32 v2, v83
	v_mov_b32_e32 v3, v91
	v_mov_b32_e32 v0, v82
	v_mov_b32_e32 v1, v90
	s_nop 0
	v_pk_fma_f32 v[36:37], v[244:245], v[26:27], v[36:37]
	v_pk_fma_f32 v[38:39], v[246:247], v[44:45], v[38:39]
	global_store_dwordx4 v[56:57], v[36:39], off offset:1024 nt
	s_nop 0
	v_pk_mul_f32 v[2:3], v[2:3], v[2:3]
	v_add_f32_e32 v26, 1.0, v41
	v_pk_fma_f32 v[0:1], v[0:1], v[0:1], v[2:3]
	v_mul_f32_e32 v3, 0xbfb8aa3b, v5
	v_exp_f32_e32 v3, v3
	v_mul_f32_e32 v2, 0xbfb8aa3b, v4
	v_pk_add_f32 v[4:5], v[0:1], v[0:1] op_sel:[0,1] op_sel_hi:[1,0]
	v_exp_f32_e32 v2, v2
	v_add_f32_e32 v1, 1.0, v3
	v_mul_f32_e32 v3, 0xbfb8aa3b, v6
	v_exp_f32_e32 v5, v3
	v_mul_f32_e32 v3, 0xbfb8aa3b, v7
	v_exp_f32_e32 v7, v3
	v_pk_add_f32 v[44:45], v[30:31], v[30:31] op_sel:[0,1] op_sel_hi:[1,0]
	v_mul_f32_e32 v30, 0xbfb8aa3b, v46
	v_rcp_f32_e32 v43, v26
	v_exp_f32_e32 v31, v30
	v_mul_f32_e32 v30, 0xbfb8aa3b, v47
	v_exp_f32_e32 v41, v30
	v_add_f32_e32 v0, 1.0, v2
	v_add_f32_e32 v5, 1.0, v5
	v_rcp_f32_e32 v0, v0
	v_rcp_f32_e32 v1, v1
	v_rcp_f32_e32 v6, v5
	v_add_f32_e32 v5, 1.0, v7
	v_lshlrev_b32_e32 v26, 16, v98
	v_and_b32_e32 v27, 0xffff0000, v98
	v_rcp_f32_e32 v7, v5
	v_pk_mul_f32 v[26:27], v[42:43], v[26:27]
	v_add_f32_e32 v31, 1.0, v31
	v_mul_f32_e32 v30, v27, v27
	v_rcp_f32_e32 v42, v31
	v_add_f32_e32 v31, 1.0, v41
	v_lshlrev_b32_e32 v2, 16, v92
	v_and_b32_e32 v3, 0xffff0000, v92
	v_rcp_f32_e32 v43, v31
	v_pk_fma_f32 v[46:47], v[26:27], v[26:27], v[30:31] op_sel_hi:[1,1,0]
	v_lshlrev_b32_e32 v30, 16, v99
	v_and_b32_e32 v31, 0xffff0000, v99
	v_pk_mul_f32 v[98:99], v[0:1], v[2:3]
	v_lshlrev_b32_e32 v0, 16, v93
	v_and_b32_e32 v1, 0xffff0000, v93
	v_pk_mul_f32 v[6:7], v[6:7], v[0:1]
	v_lshlrev_b32_e32 v0, 16, v80
	v_and_b32_e32 v1, 0xffff0000, v80
	v_lshlrev_b32_e32 v2, 16, v81
	v_and_b32_e32 v3, 0xffff0000, v81
	v_pk_mul_f32 v[28:29], v[28:29], v[88:89] op_sel_hi:[1,0]
	v_pk_mul_f32 v[20:21], v[20:21], v[88:89] op_sel_hi:[1,0]
	v_mul_f32_e32 v5, 0xbfb8aa3b, v8
	v_exp_f32_e32 v5, v5
	v_mul_f32_e32 v8, 0xbfb8aa3b, v9
	v_mov_b32_e32 v92, v98
	v_mov_b32_e32 v93, v6
	v_add_f32_e32 v5, 1.0, v5
	v_lshlrev_b32_e32 v80, 16, v85
	v_and_b32_e32 v81, 0xffff0000, v85
	v_pk_mul_f32 v[30:31], v[42:43], v[30:31]
	s_nop 0
	v_pk_fma_f32 v[0:1], v[248:249], v[20:21], v[0:1]
	v_pk_fma_f32 v[2:3], v[250:251], v[28:29], v[2:3]
	global_store_dwordx4 v[56:57], v[0:3], off offset:2048 nt
	s_nop 0
	v_exp_f32_e32 v28, v8
	v_mov_b32_e32 v20, v99
	v_mov_b32_e32 v21, v7
	v_pk_mul_f32 v[20:21], v[20:21], v[20:21]
	v_and_b32_e32 v29, 0xffff0000, v86
	v_pk_fma_f32 v[8:9], v[92:93], v[92:93], v[20:21]
	v_rcp_f32_e32 v20, v5
	v_add_f32_e32 v5, 1.0, v28
	v_rcp_f32_e32 v21, v5
	v_pk_add_f32 v[8:9], v[8:9], v[8:9] op_sel:[0,1] op_sel_hi:[1,0]
	v_mul_f32_e32 v5, 0xbfb8aa3b, v10
	v_exp_f32_e32 v5, v5
	v_mul_f32_e32 v9, 0xbfb8aa3b, v11
	v_exp_f32_e32 v9, v9
	v_lshlrev_b32_e32 v28, 16, v86
	v_add_f32_e32 v5, 1.0, v5
	v_pk_mul_f32 v[20:21], v[20:21], v[28:29]
	v_rcp_f32_e32 v28, v5
	v_add_f32_e32 v5, 1.0, v9
	v_rcp_f32_e32 v29, v5
; __device__ __forceinline__ float bf2f(unsigned b) { return __uint_as_float(b << 16); }
; __device__ __forceinline__ float sigmoidf_(float x) { return __builtin_amdgcn_rcpf(1.f + __expf(-x)); }
; __device__ __forceinline__ void row_final2(const FinPtrs (&r)[NR], const float* g, int lane) {
;     ...
;         for (int j = 0; j < 4; ++j) {
;             f32x4 pe, gl;
;             { const u32x2 a = ra[k][j]; pe = (f32x4){bf2f(a.x & 0xffffu), bf2f(a.x >> 16), bf2f(a.y & 0xffffu), bf2f(a.y >> 16)}; }
;             if (r[k].gls == nullptr) { const u32x2 b = rb[k][j]; gl = (f32x4){bf2f(b.x & 0xffffu), bf2f(b.x >> 16), bf2f(b.y & 0xffffu), bf2f(b.y >> 16)}; }
;             else { const float* gls = r[k].gls;
;                 gl = (((const f32x4*)gls)[lane + 64 * j] + ((const f32x4*)(gls + (size_t)TS * D))[lane + 64 * j]) + (((const f32x4*)(gls + (size_t)2 * TS * D))[lane + 64 * j] + ((const f32x4*)(gls + (size_t)3 * TS * D))[lane + 64 * j]); }
;             z[k][j] = (f32x4){pe.x * sigmoidf_(gl.x), pe.y * sigmoidf_(gl.y), pe.z * sigmoidf_(gl.z), pe.w * sigmoidf_(gl.w)};
;             ss[k] += (z[k][j].x * z[k][j].x + z[k][j].y * z[k][j].y) + (z[k][j].z * z[k][j].z + z[k][j].w * z[k][j].w);
;         } }
; #pragma unroll
;     for (int o = 1; o < 64; o <<= 1) {
; #pragma unroll
;             for (int k = 0; k < NR; ++k) ss[k] += __shfl_xor(ss[k], o); }
	v_mul_f32_e32 v5, 0xbfb8aa3b, v12
	v_exp_f32_e32 v5, v5
	v_mul_f32_e32 v9, 0xbfb8aa3b, v13
	v_exp_f32_e32 v9, v9
	v_lshlrev_b32_e32 v36, 16, v87
	v_and_b32_e32 v37, 0xffff0000, v87
	v_pk_mul_f32 v[28:29], v[28:29], v[36:37]
	v_add_f32_e32 v5, 1.0, v5
	v_mul_f32_e32 v36, v29, v29
	v_pk_fma_f32 v[12:13], v[28:29], v[28:29], v[36:37] op_sel_hi:[1,1,0]
	v_rcp_f32_e32 v36, v5
	v_add_f32_e32 v5, 1.0, v9
	v_rcp_f32_e32 v37, v5
	v_mul_f32_e32 v5, 0xbfb8aa3b, v14
	v_exp_f32_e32 v5, v5
	v_mul_f32_e32 v9, 0xbfb8aa3b, v15
	v_exp_f32_e32 v9, v9
	v_lshlrev_b32_e32 v38, 16, v84
	v_and_b32_e32 v39, 0xffff0000, v84
	v_add_f32_e32 v5, 1.0, v5
	v_pk_mul_f32 v[14:15], v[36:37], v[38:39]
	v_rcp_f32_e32 v36, v5
	v_add_f32_e32 v5, 1.0, v9
	v_rcp_f32_e32 v37, v5
	v_mul_f32_e32 v10, v21, v21
	v_pk_fma_f32 v[10:11], v[20:21], v[20:21], v[10:11] op_sel_hi:[1,1,0]
	v_pk_mul_f32 v[38:39], v[14:15], v[14:15]
	v_pk_mul_f32 v[36:37], v[36:37], v[80:81]
	v_mov_b32_e32 v5, v38
	v_pk_mul_f32 v[80:81], v[36:37], v[36:37]
	v_mov_b32_e32 v9, v39
	v_mov_b32_e32 v11, v80
	v_mov_b32_e32 v13, v81
	v_pk_add_f32 v[4:5], v[4:5], v[8:9]
	v_pk_add_f32 v[8:9], v[10:11], v[12:13]
	v_mul_f32_e32 v11, 0xbfb8aa3b, v32
	v_exp_f32_e32 v12, v11
	v_mul_f32_e32 v11, 0xbfb8aa3b, v33
	v_pk_add_f32 v[4:5], v[4:5], v[8:9]
	v_lshlrev_b32_e32 v8, 16, v74
	v_and_b32_e32 v9, 0xffff0000, v74
	v_lshlrev_b32_e32 v10, 16, v75
	v_exp_f32_e32 v13, v11
	v_and_b32_e32 v11, 0xffff0000, v75
	v_pk_mul_f32 v[38:39], v[96:97], v[88:89] op_sel_hi:[1,0]
	v_pk_mul_f32 v[74:75], v[104:105], v[88:89] op_sel_hi:[1,0]
	v_mul_f32_e32 v33, 0xbfb8aa3b, v34
	v_add_f32_e32 v12, 1.0, v12
	v_add_f32_e32 v13, 1.0, v13
	v_rcp_f32_e32 v12, v12
	v_rcp_f32_e32 v13, v13
	v_lshlrev_b32_e32 v32, 16, v94
	v_mul_f32_e32 v42, v31, v31
	v_pk_fma_f32 v[42:43], v[30:31], v[30:31], v[42:43] op_sel_hi:[1,1,0]
	s_nop 0
	v_pk_fma_f32 v[0:1], v[252:253], v[74:75], v[8:9]
	v_pk_fma_f32 v[2:3], v[254:255], v[38:39], v[10:11]
	global_store_dwordx4 v[56:57], v[0:3], off offset:3072 nt
	s_nop 0
	v_mul_f32_e32 v9, 0xbfb8aa3b, v35
	v_exp_f32_e32 v8, v33
	v_exp_f32_e32 v9, v9
	v_and_b32_e32 v33, 0xffff0000, v94
	v_pk_mul_f32 v[10:11], v[12:13], v[32:33]
	v_add_f32_e32 v8, 1.0, v8
	v_add_f32_e32 v9, 1.0, v9
	v_rcp_f32_e32 v8, v8
	v_rcp_f32_e32 v9, v9
	v_lshlrev_b32_e32 v12, 16, v95
	v_and_b32_e32 v13, 0xffff0000, v95
	v_lshl_add_u64 v[34:35], v[54:55], 0, s[0:1]
	v_pk_mul_f32 v[8:9], v[8:9], v[12:13]
	v_pk_mul_f32 v[12:13], v[10:11], v[10:11]
	v_pk_mul_f32 v[32:33], v[8:9], v[8:9]
	v_mov_b32_e32 v41, v12
	v_mov_b32_e32 v45, v13
	v_mov_b32_e32 v47, v32
	v_mov_b32_e32 v43, v33
	v_pk_add_f32 v[12:13], v[40:41], v[44:45]
	v_pk_add_f32 v[32:33], v[46:47], v[42:43]
	s_lshl_b64 s[0:1], s[12:13], 12
	v_pk_add_f32 v[12:13], v[12:13], v[32:33]
	v_mov_b32_e32 v33, v4
	v_mov_b32_e32 v32, v12
	v_mov_b32_e32 v4, v13
	v_pk_add_f32 v[4:5], v[32:33], v[4:5]
	ds_bpermute_b32 v13, v49, v5
	ds_bpermute_b32 v12, v49, v4
	v_lshlrev_b32_e32 v32, 16, v62
	v_and_b32_e32 v33, 0xffff0000, v62
	s_cmpk_lt_i32 s34, 0x4200
	v_lshl_add_u64 v[56:57], v[56:57], 0, s[6:7]
	s_waitcnt lgkmcnt(0)
	v_pk_add_f32 v[4:5], v[4:5], v[12:13]
	ds_bpermute_b32 v13, v51, v5
	ds_bpermute_b32 v12, v51, v4
	s_waitcnt lgkmcnt(0)
	v_pk_add_f32 v[4:5], v[4:5], v[12:13]
	ds_bpermute_b32 v13, v61, v5
	ds_bpermute_b32 v12, v61, v4
	s_waitcnt lgkmcnt(0)
	v_pk_add_f32 v[4:5], v[4:5], v[12:13]
	ds_bpermute_b32 v13, v112, v5
	ds_bpermute_b32 v12, v112, v4
	s_waitcnt lgkmcnt(0)
	v_pk_add_f32 v[4:5], v[4:5], v[12:13]
	ds_bpermute_b32 v13, v113, v5
	ds_bpermute_b32 v12, v113, v4
	s_waitcnt lgkmcnt(0)
	v_pk_add_f32 v[4:5], v[4:5], v[12:13]
	ds_bpermute_b32 v13, v114, v5
	ds_bpermute_b32 v12, v114, v4
	s_waitcnt lgkmcnt(0)
; __device__ __forceinline__ void row_final2(const FinPtrs (&r)[NR], const float* g, int lane) {
;     ...
; #pragma unroll
;     for (int k = 0; k < NR; ++k) { const float rs = rsqrtf(ss[k] * (1.f / D) + EPS);
; #pragma unroll
;         for (int j = 0; j < 4; ++j) { const f32x4 gv = ((const f32x4*)g)[lane + 64 * j]; ((f32x4*)r[k].yout)[lane + 64 * j] = x[k][j] + z[k][j] * rs * gv; } }
	v_pk_add_f32 v[4:5], v[4:5], v[12:13]
	s_nop 0
	v_pk_fma_f32 v[4:5], v[4:5], s[8:9], v[60:61] op_sel_hi:[1,0,0]
	v_and_b32_e32 v13, 0xffff0000, v63
	v_mul_f32_e32 v12, 0x4b800000, v5
	v_cmp_gt_f32_e32 vcc, s9, v5
	s_nop 1
	v_cndmask_b32_e32 v5, v5, v12, vcc
	v_rsq_f32_e32 v5, v5
	v_lshlrev_b32_e32 v12, 16, v63
	v_mul_f32_e32 v38, 0x45800000, v5
	v_cndmask_b32_e32 v38, v5, v38, vcc
	v_pk_mul_f32 v[40:41], v[90:91], v[38:39] op_sel_hi:[1,0]
	v_pk_mul_f32 v[42:43], v[82:83], v[38:39] op_sel_hi:[1,0]
	s_nop 0
	v_pk_fma_f32 v[2:3], v[242:243], v[40:41], v[12:13]
	v_pk_fma_f32 v[0:1], v[240:241], v[42:43], v[32:33]
	global_store_dwordx4 v[34:35], v[0:3], off nt
	s_nop 0
	v_lshlrev_b32_e32 v12, 16, v66
	v_and_b32_e32 v13, 0xffff0000, v66
	v_lshlrev_b32_e32 v32, 16, v67
	v_and_b32_e32 v33, 0xffff0000, v67
	v_pk_mul_f32 v[6:7], v[6:7], v[38:39] op_sel_hi:[1,0]
	v_pk_mul_f32 v[40:41], v[98:99], v[38:39] op_sel_hi:[1,0]
	v_pk_mul_f32 v[28:29], v[28:29], v[38:39] op_sel_hi:[1,0]
	v_pk_mul_f32 v[20:21], v[20:21], v[38:39] op_sel_hi:[1,0]
	v_pk_mul_f32 v[14:15], v[14:15], v[38:39] op_sel_hi:[1,0]
	v_mul_f32_e32 v5, 0x4b800000, v4
	v_cmp_gt_f32_e32 vcc, s9, v4
	s_nop 0
	v_pk_fma_f32 v[0:1], v[40:41], v[244:245], v[12:13]
	v_pk_fma_f32 v[2:3], v[6:7], v[246:247], v[32:33]
	global_store_dwordx4 v[34:35], v[0:3], off offset:1024 nt
	s_nop 0
	v_lshlrev_b32_e32 v6, 16, v68
	v_and_b32_e32 v7, 0xffff0000, v68
	v_lshlrev_b32_e32 v12, 16, v69
	v_and_b32_e32 v13, 0xffff0000, v69
	v_cndmask_b32_e32 v4, v4, v5, vcc
	v_and_b32_e32 v5, 0xffff0000, v71
	s_nop 0
	v_pk_fma_f32 v[0:1], v[20:21], v[248:249], v[6:7]
	v_pk_fma_f32 v[2:3], v[28:29], v[250:251], v[12:13]
	global_store_dwordx4 v[34:35], v[0:3], off offset:2048 nt
	s_nop 0
	v_lshlrev_b32_e32 v6, 16, v64
	v_and_b32_e32 v7, 0xffff0000, v64
	v_lshlrev_b32_e32 v12, 16, v65
	v_and_b32_e32 v13, 0xffff0000, v65
	v_pk_mul_f32 v[20:21], v[36:37], v[38:39] op_sel_hi:[1,0]
	s_nop 0
	v_pk_fma_f32 v[0:1], v[14:15], v[252:253], v[6:7]
	v_pk_fma_f32 v[2:3], v[20:21], v[254:255], v[12:13]
	global_store_dwordx4 v[34:35], v[0:3], off offset:3072 nt
	s_nop 0
	v_rsq_f32_e32 v14, v4
	v_lshlrev_b32_e32 v6, 16, v70
	v_and_b32_e32 v7, 0xffff0000, v70
	v_lshlrev_b32_e32 v4, 16, v71
	v_mul_f32_e32 v15, 0x45800000, v14
	v_cndmask_b32_e32 v14, v14, v15, vcc
	v_pk_mul_f32 v[18:19], v[18:19], v[14:15] op_sel_hi:[1,0]
	v_pk_mul_f32 v[16:17], v[16:17], v[14:15] op_sel_hi:[1,0]
	v_lshl_add_u64 v[12:13], v[54:55], 0, s[0:1]
	v_pk_mul_f32 v[8:9], v[8:9], v[14:15] op_sel_hi:[1,0]
	v_pk_mul_f32 v[10:11], v[10:11], v[14:15] op_sel_hi:[1,0]
	s_nop 0
	v_pk_fma_f32 v[0:1], v[16:17], v[240:241], v[6:7]
	v_pk_fma_f32 v[2:3], v[18:19], v[242:243], v[4:5]
	global_store_dwordx4 v[12:13], v[0:3], off nt
	s_nop 0
	v_lshlrev_b32_e32 v4, 16, v78
	v_and_b32_e32 v5, 0xffff0000, v78
	v_lshlrev_b32_e32 v6, 16, v79
	v_and_b32_e32 v7, 0xffff0000, v79
	v_pk_mul_f32 v[16:17], v[24:25], v[14:15] op_sel_hi:[1,0]
	v_pk_mul_f32 v[18:19], v[22:23], v[14:15] op_sel_hi:[1,0]
	s_nop 0
	v_pk_fma_f32 v[2:3], v[16:17], v[246:247], v[6:7]
	v_pk_fma_f32 v[0:1], v[18:19], v[244:245], v[4:5]
	global_store_dwordx4 v[12:13], v[0:3], off offset:1024 nt
	s_nop 0
	v_lshlrev_b32_e32 v4, 16, v76
	v_and_b32_e32 v5, 0xffff0000, v76
	v_lshlrev_b32_e32 v6, 16, v77
	v_and_b32_e32 v7, 0xffff0000, v77
	v_pk_mul_f32 v[16:17], v[30:31], v[14:15] op_sel_hi:[1,0]
	v_pk_mul_f32 v[18:19], v[26:27], v[14:15] op_sel_hi:[1,0]
	s_nop 0
	v_pk_fma_f32 v[2:3], v[16:17], v[250:251], v[6:7]
	v_pk_fma_f32 v[0:1], v[18:19], v[248:249], v[4:5]
	global_store_dwordx4 v[12:13], v[0:3], off offset:2048 nt
	s_nop 0
	v_lshlrev_b32_e32 v4, 16, v72
	v_and_b32_e32 v5, 0xffff0000, v72
	v_lshlrev_b32_e32 v6, 16, v73
	v_and_b32_e32 v7, 0xffff0000, v73
	s_nop 0
	v_pk_fma_f32 v[0:1], v[10:11], v[252:253], v[4:5]
	v_pk_fma_f32 v[2:3], v[8:9], v[254:255], v[6:7]
	global_store_dwordx4 v[12:13], v[0:3], off offset:3072 nt
	s_cbranch_scc0 .LBB0_1282
